# v68 + P6 epilogue: residual loads up front and full-128-byte-line output stores
# speedup vs baseline: 1.0073x; 1.0007x over previous
.LBB0_761:
	v_lshl_add_u32 v148, s26, 8, v150
	v_lshl_or_b32 v146, s52, 8, v152
	v_lshl_add_u32 v144, v148, 10, v146
	v_lshlrev_b32_e32 v224, 1, v144
	v_add_u32_e32 v225, 0x8000, v224
	v_add_u32_e32 v226, 0x10000, v224
	v_add_u32_e32 v227, 0x18000, v224
	v_add_u32_e32 v228, 0x40000, v224
	v_add_u32_e32 v229, 0x48000, v224
	v_add_u32_e32 v230, 0x50000, v224
	v_add_u32_e32 v231, 0x58000, v224
	global_load_dwordx4 v[160:163], v224, s[36:37]
	global_load_dwordx4 v[164:167], v224, s[36:37] offset:256
	global_load_dwordx4 v[168:171], v225, s[36:37]
	global_load_dwordx4 v[172:175], v225, s[36:37] offset:256
	global_load_dwordx4 v[176:179], v226, s[36:37]
	global_load_dwordx4 v[180:183], v226, s[36:37] offset:256
	global_load_dwordx4 v[184:187], v227, s[36:37]
	global_load_dwordx4 v[188:191], v227, s[36:37] offset:256
	global_load_dwordx4 v[192:195], v228, s[36:37]
	global_load_dwordx4 v[196:199], v228, s[36:37] offset:256
	global_load_dwordx4 v[200:203], v229, s[36:37]
	global_load_dwordx4 v[204:207], v229, s[36:37] offset:256
	global_load_dwordx4 v[208:211], v230, s[36:37]
	global_load_dwordx4 v[212:215], v230, s[36:37] offset:256
	global_load_dwordx4 v[216:219], v231, s[36:37]
	global_load_dwordx4 v[220:223], v231, s[36:37] offset:256
	v_mbcnt_lo_u32_b32 v145, -1, 0
	v_mbcnt_hi_u32_b32 v145, -1, v145
	v_and_b32_e32 v145, 8, v145
	v_mul_u32_u24_e32 v147, 0xffe, v145
	v_lshlrev_b32_e32 v232, 2, v144
	v_sub_u32_e32 v232, v232, v147
	v_add_u32_e32 v233, 0x10000, v232
	v_add_u32_e32 v234, 0x20000, v232
	v_add_u32_e32 v235, 0x30000, v232
	v_add_u32_e32 v236, 0x80000, v232
	v_add_u32_e32 v237, 0x90000, v232
	v_add_u32_e32 v238, 0xa0000, v232
	v_add_u32_e32 v239, 0xb0000, v232
	s_mov_b32 s40, 0x00ff00ff
	s_mov_b32 s41, 0x00ff00ff
	s_andn2_b64 vcc, exec, s[0:1]
	s_mov_b64 s[0:1], -1
	s_waitcnt vmcnt(15)
	v_lshlrev_b32_e32 v156, 16, v160
	v_and_b32_e32 v157, 0xffff0000, v160
	v_lshlrev_b32_e32 v160, 16, v161
	v_and_b32_e32 v161, 0xffff0000, v161
	v_lshlrev_b32_e32 v158, 16, v162
	v_and_b32_e32 v159, 0xffff0000, v162
	v_lshlrev_b32_e32 v162, 16, v163
	v_and_b32_e32 v163, 0xffff0000, v163
	v_pk_add_f32 v[126:127], v[126:127], v[160:161]
	v_pk_add_f32 v[124:125], v[124:125], v[156:157]
	v_pk_add_f32 v[122:123], v[122:123], v[162:163]
	v_pk_add_f32 v[120:121], v[120:121], v[158:159]
	v_add_u32_e32 v149, 0x8000, v232
	s_nop 0
	v_mov_b32_dpp v160, v120 row_ror:8 row_mask:0xf bank_mask:0xf
	v_mov_b32_dpp v161, v121 row_ror:8 row_mask:0xf bank_mask:0xf
	v_mov_b32_dpp v162, v122 row_ror:8 row_mask:0xf bank_mask:0xf
	v_mov_b32_dpp v163, v123 row_ror:8 row_mask:0xf bank_mask:0xf
	v_mov_b32_dpp v156, v124 row_ror:8 row_mask:0xf bank_mask:0xf
	v_mov_b32_dpp v157, v125 row_ror:8 row_mask:0xf bank_mask:0xf
	v_mov_b32_dpp v158, v126 row_ror:8 row_mask:0xf bank_mask:0xf
	v_mov_b32_dpp v159, v127 row_ror:8 row_mask:0xf bank_mask:0xf
	v_cndmask_b32_e64 v160, v160, v124, s[40:41]
	v_cndmask_b32_e64 v161, v161, v125, s[40:41]
	v_cndmask_b32_e64 v162, v162, v126, s[40:41]
	v_cndmask_b32_e64 v163, v163, v127, s[40:41]
	v_cndmask_b32_e64 v156, v120, v156, s[40:41]
	v_cndmask_b32_e64 v157, v121, v157, s[40:41]
	v_cndmask_b32_e64 v158, v122, v158, s[40:41]
	v_cndmask_b32_e64 v159, v123, v159, s[40:41]
	global_store_dwordx4 v232, v[160:163], s[30:31] nt
	global_store_dwordx4 v149, v[156:159], s[30:31] nt
	s_nop 1
	s_waitcnt vmcnt(16)
	v_lshlrev_b32_e32 v156, 16, v164
	v_and_b32_e32 v157, 0xffff0000, v164
	v_lshlrev_b32_e32 v164, 16, v165
	v_and_b32_e32 v165, 0xffff0000, v165
	v_lshlrev_b32_e32 v158, 16, v166
	v_and_b32_e32 v159, 0xffff0000, v166
	v_lshlrev_b32_e32 v166, 16, v167
	v_and_b32_e32 v167, 0xffff0000, v167
	v_pk_add_f32 v[118:119], v[118:119], v[164:165]
	v_pk_add_f32 v[116:117], v[116:117], v[156:157]
	v_pk_add_f32 v[114:115], v[114:115], v[166:167]
	v_pk_add_f32 v[112:113], v[112:113], v[158:159]
	v_add_u32_e32 v149, 0x8000, v232
	s_nop 0
	v_mov_b32_dpp v164, v112 row_ror:8 row_mask:0xf bank_mask:0xf
	v_mov_b32_dpp v165, v113 row_ror:8 row_mask:0xf bank_mask:0xf
	v_mov_b32_dpp v166, v114 row_ror:8 row_mask:0xf bank_mask:0xf
	v_mov_b32_dpp v167, v115 row_ror:8 row_mask:0xf bank_mask:0xf
	v_mov_b32_dpp v156, v116 row_ror:8 row_mask:0xf bank_mask:0xf
	v_mov_b32_dpp v157, v117 row_ror:8 row_mask:0xf bank_mask:0xf
	v_mov_b32_dpp v158, v118 row_ror:8 row_mask:0xf bank_mask:0xf
	v_mov_b32_dpp v159, v119 row_ror:8 row_mask:0xf bank_mask:0xf
	v_cndmask_b32_e64 v164, v164, v116, s[40:41]
	v_cndmask_b32_e64 v165, v165, v117, s[40:41]
	v_cndmask_b32_e64 v166, v166, v118, s[40:41]
	v_cndmask_b32_e64 v167, v167, v119, s[40:41]
	v_cndmask_b32_e64 v156, v112, v156, s[40:41]
	v_cndmask_b32_e64 v157, v113, v157, s[40:41]
	v_cndmask_b32_e64 v158, v114, v158, s[40:41]
	v_cndmask_b32_e64 v159, v115, v159, s[40:41]
	global_store_dwordx4 v232, v[164:167], s[30:31] offset:512 nt
	global_store_dwordx4 v149, v[156:159], s[30:31] offset:512 nt
	s_nop 1
	s_waitcnt vmcnt(17)
	v_lshlrev_b32_e32 v156, 16, v168
	v_and_b32_e32 v157, 0xffff0000, v168
	v_lshlrev_b32_e32 v168, 16, v169
	v_and_b32_e32 v169, 0xffff0000, v169
	v_lshlrev_b32_e32 v158, 16, v170
	v_and_b32_e32 v159, 0xffff0000, v170
	v_lshlrev_b32_e32 v170, 16, v171
	v_and_b32_e32 v171, 0xffff0000, v171
	v_pk_add_f32 v[110:111], v[110:111], v[168:169]
	v_pk_add_f32 v[108:109], v[108:109], v[156:157]
	v_pk_add_f32 v[106:107], v[106:107], v[170:171]
	v_pk_add_f32 v[104:105], v[104:105], v[158:159]
	v_add_u32_e32 v149, 0x8000, v233
	s_nop 0
	v_mov_b32_dpp v168, v104 row_ror:8 row_mask:0xf bank_mask:0xf
	v_mov_b32_dpp v169, v105 row_ror:8 row_mask:0xf bank_mask:0xf
	v_mov_b32_dpp v170, v106 row_ror:8 row_mask:0xf bank_mask:0xf
	v_mov_b32_dpp v171, v107 row_ror:8 row_mask:0xf bank_mask:0xf
	v_mov_b32_dpp v156, v108 row_ror:8 row_mask:0xf bank_mask:0xf
	v_mov_b32_dpp v157, v109 row_ror:8 row_mask:0xf bank_mask:0xf
	v_mov_b32_dpp v158, v110 row_ror:8 row_mask:0xf bank_mask:0xf
	v_mov_b32_dpp v159, v111 row_ror:8 row_mask:0xf bank_mask:0xf
	v_cndmask_b32_e64 v168, v168, v108, s[40:41]
	v_cndmask_b32_e64 v169, v169, v109, s[40:41]
	v_cndmask_b32_e64 v170, v170, v110, s[40:41]
	v_cndmask_b32_e64 v171, v171, v111, s[40:41]
	v_cndmask_b32_e64 v156, v104, v156, s[40:41]
	v_cndmask_b32_e64 v157, v105, v157, s[40:41]
	v_cndmask_b32_e64 v158, v106, v158, s[40:41]
	v_cndmask_b32_e64 v159, v107, v159, s[40:41]
	global_store_dwordx4 v233, v[168:171], s[30:31] nt
	global_store_dwordx4 v149, v[156:159], s[30:31] nt
	s_nop 1
	s_waitcnt vmcnt(18)
	v_lshlrev_b32_e32 v156, 16, v172
	v_and_b32_e32 v157, 0xffff0000, v172
	v_lshlrev_b32_e32 v172, 16, v173
	v_and_b32_e32 v173, 0xffff0000, v173
	v_lshlrev_b32_e32 v158, 16, v174
	v_and_b32_e32 v159, 0xffff0000, v174
	v_lshlrev_b32_e32 v174, 16, v175
	v_and_b32_e32 v175, 0xffff0000, v175
	v_pk_add_f32 v[102:103], v[102:103], v[172:173]
	v_pk_add_f32 v[100:101], v[100:101], v[156:157]
	v_pk_add_f32 v[98:99], v[98:99], v[174:175]
	v_pk_add_f32 v[96:97], v[96:97], v[158:159]
	v_add_u32_e32 v149, 0x8000, v233
	s_nop 0
	v_mov_b32_dpp v172, v96 row_ror:8 row_mask:0xf bank_mask:0xf
	v_mov_b32_dpp v173, v97 row_ror:8 row_mask:0xf bank_mask:0xf
	v_mov_b32_dpp v174, v98 row_ror:8 row_mask:0xf bank_mask:0xf
	v_mov_b32_dpp v175, v99 row_ror:8 row_mask:0xf bank_mask:0xf
	v_mov_b32_dpp v156, v100 row_ror:8 row_mask:0xf bank_mask:0xf
	v_mov_b32_dpp v157, v101 row_ror:8 row_mask:0xf bank_mask:0xf
	v_mov_b32_dpp v158, v102 row_ror:8 row_mask:0xf bank_mask:0xf
	v_mov_b32_dpp v159, v103 row_ror:8 row_mask:0xf bank_mask:0xf
	v_cndmask_b32_e64 v172, v172, v100, s[40:41]
	v_cndmask_b32_e64 v173, v173, v101, s[40:41]
	v_cndmask_b32_e64 v174, v174, v102, s[40:41]
	v_cndmask_b32_e64 v175, v175, v103, s[40:41]
	v_cndmask_b32_e64 v156, v96, v156, s[40:41]
	v_cndmask_b32_e64 v157, v97, v157, s[40:41]
	v_cndmask_b32_e64 v158, v98, v158, s[40:41]
	v_cndmask_b32_e64 v159, v99, v159, s[40:41]
	global_store_dwordx4 v233, v[172:175], s[30:31] offset:512 nt
	global_store_dwordx4 v149, v[156:159], s[30:31] offset:512 nt
	s_nop 1
	s_waitcnt vmcnt(19)
	v_lshlrev_b32_e32 v156, 16, v176
	v_and_b32_e32 v157, 0xffff0000, v176
	v_lshlrev_b32_e32 v176, 16, v177
	v_and_b32_e32 v177, 0xffff0000, v177
	v_lshlrev_b32_e32 v158, 16, v178
	v_and_b32_e32 v159, 0xffff0000, v178
	v_lshlrev_b32_e32 v178, 16, v179
	v_and_b32_e32 v179, 0xffff0000, v179
	v_pk_add_f32 v[94:95], v[94:95], v[176:177]
	v_pk_add_f32 v[92:93], v[92:93], v[156:157]
	v_pk_add_f32 v[90:91], v[90:91], v[178:179]
	v_pk_add_f32 v[88:89], v[88:89], v[158:159]
	v_add_u32_e32 v149, 0x8000, v234
	s_nop 0
	v_mov_b32_dpp v176, v88 row_ror:8 row_mask:0xf bank_mask:0xf
	v_mov_b32_dpp v177, v89 row_ror:8 row_mask:0xf bank_mask:0xf
	v_mov_b32_dpp v178, v90 row_ror:8 row_mask:0xf bank_mask:0xf
	v_mov_b32_dpp v179, v91 row_ror:8 row_mask:0xf bank_mask:0xf
	v_mov_b32_dpp v156, v92 row_ror:8 row_mask:0xf bank_mask:0xf
	v_mov_b32_dpp v157, v93 row_ror:8 row_mask:0xf bank_mask:0xf
	v_mov_b32_dpp v158, v94 row_ror:8 row_mask:0xf bank_mask:0xf
	v_mov_b32_dpp v159, v95 row_ror:8 row_mask:0xf bank_mask:0xf
	v_cndmask_b32_e64 v176, v176, v92, s[40:41]
	v_cndmask_b32_e64 v177, v177, v93, s[40:41]
	v_cndmask_b32_e64 v178, v178, v94, s[40:41]
	v_cndmask_b32_e64 v179, v179, v95, s[40:41]
	v_cndmask_b32_e64 v156, v88, v156, s[40:41]
	v_cndmask_b32_e64 v157, v89, v157, s[40:41]
	v_cndmask_b32_e64 v158, v90, v158, s[40:41]
	v_cndmask_b32_e64 v159, v91, v159, s[40:41]
	global_store_dwordx4 v234, v[176:179], s[30:31] nt
	global_store_dwordx4 v149, v[156:159], s[30:31] nt
	s_nop 1
	s_waitcnt vmcnt(20)
	v_lshlrev_b32_e32 v156, 16, v180
	v_and_b32_e32 v157, 0xffff0000, v180
	v_lshlrev_b32_e32 v180, 16, v181
	v_and_b32_e32 v181, 0xffff0000, v181
	v_lshlrev_b32_e32 v158, 16, v182
	v_and_b32_e32 v159, 0xffff0000, v182
	v_lshlrev_b32_e32 v182, 16, v183
	v_and_b32_e32 v183, 0xffff0000, v183
	v_pk_add_f32 v[86:87], v[86:87], v[180:181]
	v_pk_add_f32 v[84:85], v[84:85], v[156:157]
	v_pk_add_f32 v[82:83], v[82:83], v[182:183]
	v_pk_add_f32 v[80:81], v[80:81], v[158:159]
	v_add_u32_e32 v149, 0x8000, v234
	s_nop 0
	v_mov_b32_dpp v180, v80 row_ror:8 row_mask:0xf bank_mask:0xf
	v_mov_b32_dpp v181, v81 row_ror:8 row_mask:0xf bank_mask:0xf
	v_mov_b32_dpp v182, v82 row_ror:8 row_mask:0xf bank_mask:0xf
	v_mov_b32_dpp v183, v83 row_ror:8 row_mask:0xf bank_mask:0xf
	v_mov_b32_dpp v156, v84 row_ror:8 row_mask:0xf bank_mask:0xf
	v_mov_b32_dpp v157, v85 row_ror:8 row_mask:0xf bank_mask:0xf
	v_mov_b32_dpp v158, v86 row_ror:8 row_mask:0xf bank_mask:0xf
	v_mov_b32_dpp v159, v87 row_ror:8 row_mask:0xf bank_mask:0xf
	v_cndmask_b32_e64 v180, v180, v84, s[40:41]
	v_cndmask_b32_e64 v181, v181, v85, s[40:41]
	v_cndmask_b32_e64 v182, v182, v86, s[40:41]
	v_cndmask_b32_e64 v183, v183, v87, s[40:41]
	v_cndmask_b32_e64 v156, v80, v156, s[40:41]
	v_cndmask_b32_e64 v157, v81, v157, s[40:41]
	v_cndmask_b32_e64 v158, v82, v158, s[40:41]
	v_cndmask_b32_e64 v159, v83, v159, s[40:41]
	global_store_dwordx4 v234, v[180:183], s[30:31] offset:512 nt
	global_store_dwordx4 v149, v[156:159], s[30:31] offset:512 nt
	s_nop 1
	s_waitcnt vmcnt(21)
	v_lshlrev_b32_e32 v156, 16, v184
	v_and_b32_e32 v157, 0xffff0000, v184
	v_lshlrev_b32_e32 v184, 16, v185
	v_and_b32_e32 v185, 0xffff0000, v185
	v_lshlrev_b32_e32 v158, 16, v186
	v_and_b32_e32 v159, 0xffff0000, v186
	v_lshlrev_b32_e32 v186, 16, v187
	v_and_b32_e32 v187, 0xffff0000, v187
	v_pk_add_f32 v[78:79], v[78:79], v[184:185]
	v_pk_add_f32 v[76:77], v[76:77], v[156:157]
	v_pk_add_f32 v[74:75], v[74:75], v[186:187]
	v_pk_add_f32 v[72:73], v[72:73], v[158:159]
	v_add_u32_e32 v149, 0x8000, v235
	s_nop 0
	v_mov_b32_dpp v184, v72 row_ror:8 row_mask:0xf bank_mask:0xf
	v_mov_b32_dpp v185, v73 row_ror:8 row_mask:0xf bank_mask:0xf
	v_mov_b32_dpp v186, v74 row_ror:8 row_mask:0xf bank_mask:0xf
	v_mov_b32_dpp v187, v75 row_ror:8 row_mask:0xf bank_mask:0xf
	v_mov_b32_dpp v156, v76 row_ror:8 row_mask:0xf bank_mask:0xf
	v_mov_b32_dpp v157, v77 row_ror:8 row_mask:0xf bank_mask:0xf
	v_mov_b32_dpp v158, v78 row_ror:8 row_mask:0xf bank_mask:0xf
	v_mov_b32_dpp v159, v79 row_ror:8 row_mask:0xf bank_mask:0xf
	v_cndmask_b32_e64 v184, v184, v76, s[40:41]
	v_cndmask_b32_e64 v185, v185, v77, s[40:41]
	v_cndmask_b32_e64 v186, v186, v78, s[40:41]
	v_cndmask_b32_e64 v187, v187, v79, s[40:41]
	v_cndmask_b32_e64 v156, v72, v156, s[40:41]
	v_cndmask_b32_e64 v157, v73, v157, s[40:41]
	v_cndmask_b32_e64 v158, v74, v158, s[40:41]
	v_cndmask_b32_e64 v159, v75, v159, s[40:41]
	global_store_dwordx4 v235, v[184:187], s[30:31] nt
	global_store_dwordx4 v149, v[156:159], s[30:31] nt
	s_nop 1
	s_waitcnt vmcnt(22)
	v_lshlrev_b32_e32 v156, 16, v188
	v_and_b32_e32 v157, 0xffff0000, v188
	v_lshlrev_b32_e32 v188, 16, v189
	v_and_b32_e32 v189, 0xffff0000, v189
	v_lshlrev_b32_e32 v158, 16, v190
	v_and_b32_e32 v159, 0xffff0000, v190
	v_lshlrev_b32_e32 v190, 16, v191
	v_and_b32_e32 v191, 0xffff0000, v191
	v_pk_add_f32 v[70:71], v[70:71], v[188:189]
	v_pk_add_f32 v[68:69], v[68:69], v[156:157]
	v_pk_add_f32 v[66:67], v[66:67], v[190:191]
	v_pk_add_f32 v[64:65], v[64:65], v[158:159]
	v_add_u32_e32 v149, 0x8000, v235
	s_nop 0
	v_mov_b32_dpp v188, v64 row_ror:8 row_mask:0xf bank_mask:0xf
	v_mov_b32_dpp v189, v65 row_ror:8 row_mask:0xf bank_mask:0xf
	v_mov_b32_dpp v190, v66 row_ror:8 row_mask:0xf bank_mask:0xf
	v_mov_b32_dpp v191, v67 row_ror:8 row_mask:0xf bank_mask:0xf
	v_mov_b32_dpp v156, v68 row_ror:8 row_mask:0xf bank_mask:0xf
	v_mov_b32_dpp v157, v69 row_ror:8 row_mask:0xf bank_mask:0xf
	v_mov_b32_dpp v158, v70 row_ror:8 row_mask:0xf bank_mask:0xf
	v_mov_b32_dpp v159, v71 row_ror:8 row_mask:0xf bank_mask:0xf
	v_cndmask_b32_e64 v188, v188, v68, s[40:41]
	v_cndmask_b32_e64 v189, v189, v69, s[40:41]
	v_cndmask_b32_e64 v190, v190, v70, s[40:41]
	v_cndmask_b32_e64 v191, v191, v71, s[40:41]
	v_cndmask_b32_e64 v156, v64, v156, s[40:41]
	v_cndmask_b32_e64 v157, v65, v157, s[40:41]
	v_cndmask_b32_e64 v158, v66, v158, s[40:41]
	v_cndmask_b32_e64 v159, v67, v159, s[40:41]
	global_store_dwordx4 v235, v[188:191], s[30:31] offset:512 nt
	global_store_dwordx4 v149, v[156:159], s[30:31] offset:512 nt
	s_nop 1
	s_waitcnt vmcnt(23)
	v_lshlrev_b32_e32 v156, 16, v192
	v_and_b32_e32 v157, 0xffff0000, v192
	v_lshlrev_b32_e32 v192, 16, v193
	v_and_b32_e32 v193, 0xffff0000, v193
	v_lshlrev_b32_e32 v158, 16, v194
	v_and_b32_e32 v159, 0xffff0000, v194
	v_lshlrev_b32_e32 v194, 16, v195
	v_and_b32_e32 v195, 0xffff0000, v195
	v_pk_add_f32 v[62:63], v[62:63], v[192:193]
	v_pk_add_f32 v[60:61], v[60:61], v[156:157]
	v_pk_add_f32 v[58:59], v[58:59], v[194:195]
	v_pk_add_f32 v[56:57], v[56:57], v[158:159]
	v_add_u32_e32 v149, 0x8000, v236
	s_nop 0
	v_mov_b32_dpp v192, v56 row_ror:8 row_mask:0xf bank_mask:0xf
	v_mov_b32_dpp v193, v57 row_ror:8 row_mask:0xf bank_mask:0xf
	v_mov_b32_dpp v194, v58 row_ror:8 row_mask:0xf bank_mask:0xf
	v_mov_b32_dpp v195, v59 row_ror:8 row_mask:0xf bank_mask:0xf
	v_mov_b32_dpp v156, v60 row_ror:8 row_mask:0xf bank_mask:0xf
	v_mov_b32_dpp v157, v61 row_ror:8 row_mask:0xf bank_mask:0xf
	v_mov_b32_dpp v158, v62 row_ror:8 row_mask:0xf bank_mask:0xf
	v_mov_b32_dpp v159, v63 row_ror:8 row_mask:0xf bank_mask:0xf
	v_cndmask_b32_e64 v192, v192, v60, s[40:41]
	v_cndmask_b32_e64 v193, v193, v61, s[40:41]
	v_cndmask_b32_e64 v194, v194, v62, s[40:41]
	v_cndmask_b32_e64 v195, v195, v63, s[40:41]
	v_cndmask_b32_e64 v156, v56, v156, s[40:41]
	v_cndmask_b32_e64 v157, v57, v157, s[40:41]
	v_cndmask_b32_e64 v158, v58, v158, s[40:41]
	v_cndmask_b32_e64 v159, v59, v159, s[40:41]
	global_store_dwordx4 v236, v[192:195], s[30:31] nt
	global_store_dwordx4 v149, v[156:159], s[30:31] nt
	s_nop 1
	s_waitcnt vmcnt(24)
	v_lshlrev_b32_e32 v156, 16, v196
	v_and_b32_e32 v157, 0xffff0000, v196
	v_lshlrev_b32_e32 v196, 16, v197
	v_and_b32_e32 v197, 0xffff0000, v197
	v_lshlrev_b32_e32 v158, 16, v198
	v_and_b32_e32 v159, 0xffff0000, v198
	v_lshlrev_b32_e32 v198, 16, v199
	v_and_b32_e32 v199, 0xffff0000, v199
	v_pk_add_f32 v[54:55], v[54:55], v[196:197]
	v_pk_add_f32 v[52:53], v[52:53], v[156:157]
	v_pk_add_f32 v[50:51], v[50:51], v[198:199]
	v_pk_add_f32 v[48:49], v[48:49], v[158:159]
	v_add_u32_e32 v149, 0x8000, v236
	s_nop 0
	v_mov_b32_dpp v196, v48 row_ror:8 row_mask:0xf bank_mask:0xf
	v_mov_b32_dpp v197, v49 row_ror:8 row_mask:0xf bank_mask:0xf
	v_mov_b32_dpp v198, v50 row_ror:8 row_mask:0xf bank_mask:0xf
	v_mov_b32_dpp v199, v51 row_ror:8 row_mask:0xf bank_mask:0xf
	v_mov_b32_dpp v156, v52 row_ror:8 row_mask:0xf bank_mask:0xf
	v_mov_b32_dpp v157, v53 row_ror:8 row_mask:0xf bank_mask:0xf
	v_mov_b32_dpp v158, v54 row_ror:8 row_mask:0xf bank_mask:0xf
	v_mov_b32_dpp v159, v55 row_ror:8 row_mask:0xf bank_mask:0xf
	v_cndmask_b32_e64 v196, v196, v52, s[40:41]
	v_cndmask_b32_e64 v197, v197, v53, s[40:41]
	v_cndmask_b32_e64 v198, v198, v54, s[40:41]
	v_cndmask_b32_e64 v199, v199, v55, s[40:41]
	v_cndmask_b32_e64 v156, v48, v156, s[40:41]
	v_cndmask_b32_e64 v157, v49, v157, s[40:41]
	v_cndmask_b32_e64 v158, v50, v158, s[40:41]
	v_cndmask_b32_e64 v159, v51, v159, s[40:41]
	global_store_dwordx4 v236, v[196:199], s[30:31] offset:512 nt
	global_store_dwordx4 v149, v[156:159], s[30:31] offset:512 nt
	s_nop 1
	s_waitcnt vmcnt(25)
	v_lshlrev_b32_e32 v156, 16, v200
	v_and_b32_e32 v157, 0xffff0000, v200
	v_lshlrev_b32_e32 v200, 16, v201
	v_and_b32_e32 v201, 0xffff0000, v201
	v_lshlrev_b32_e32 v158, 16, v202
	v_and_b32_e32 v159, 0xffff0000, v202
	v_lshlrev_b32_e32 v202, 16, v203
	v_and_b32_e32 v203, 0xffff0000, v203
	v_pk_add_f32 v[46:47], v[46:47], v[200:201]
	v_pk_add_f32 v[44:45], v[44:45], v[156:157]
	v_pk_add_f32 v[42:43], v[42:43], v[202:203]
	v_pk_add_f32 v[40:41], v[40:41], v[158:159]
	v_add_u32_e32 v149, 0x8000, v237
	s_nop 0
	v_mov_b32_dpp v200, v40 row_ror:8 row_mask:0xf bank_mask:0xf
	v_mov_b32_dpp v201, v41 row_ror:8 row_mask:0xf bank_mask:0xf
	v_mov_b32_dpp v202, v42 row_ror:8 row_mask:0xf bank_mask:0xf
	v_mov_b32_dpp v203, v43 row_ror:8 row_mask:0xf bank_mask:0xf
	v_mov_b32_dpp v156, v44 row_ror:8 row_mask:0xf bank_mask:0xf
	v_mov_b32_dpp v157, v45 row_ror:8 row_mask:0xf bank_mask:0xf
	v_mov_b32_dpp v158, v46 row_ror:8 row_mask:0xf bank_mask:0xf
	v_mov_b32_dpp v159, v47 row_ror:8 row_mask:0xf bank_mask:0xf
	v_cndmask_b32_e64 v200, v200, v44, s[40:41]
	v_cndmask_b32_e64 v201, v201, v45, s[40:41]
	v_cndmask_b32_e64 v202, v202, v46, s[40:41]
	v_cndmask_b32_e64 v203, v203, v47, s[40:41]
	v_cndmask_b32_e64 v156, v40, v156, s[40:41]
	v_cndmask_b32_e64 v157, v41, v157, s[40:41]
	v_cndmask_b32_e64 v158, v42, v158, s[40:41]
	v_cndmask_b32_e64 v159, v43, v159, s[40:41]
	global_store_dwordx4 v237, v[200:203], s[30:31] nt
	global_store_dwordx4 v149, v[156:159], s[30:31] nt
	s_nop 1
	s_waitcnt vmcnt(26)
	v_lshlrev_b32_e32 v156, 16, v204
	v_and_b32_e32 v157, 0xffff0000, v204
	v_lshlrev_b32_e32 v204, 16, v205
	v_and_b32_e32 v205, 0xffff0000, v205
	v_lshlrev_b32_e32 v158, 16, v206
	v_and_b32_e32 v159, 0xffff0000, v206
	v_lshlrev_b32_e32 v206, 16, v207
	v_and_b32_e32 v207, 0xffff0000, v207
	v_pk_add_f32 v[38:39], v[38:39], v[204:205]
	v_pk_add_f32 v[36:37], v[36:37], v[156:157]
	v_pk_add_f32 v[34:35], v[34:35], v[206:207]
	v_pk_add_f32 v[32:33], v[32:33], v[158:159]
	v_add_u32_e32 v149, 0x8000, v237
	s_nop 0
	v_mov_b32_dpp v204, v32 row_ror:8 row_mask:0xf bank_mask:0xf
	v_mov_b32_dpp v205, v33 row_ror:8 row_mask:0xf bank_mask:0xf
	v_mov_b32_dpp v206, v34 row_ror:8 row_mask:0xf bank_mask:0xf
	v_mov_b32_dpp v207, v35 row_ror:8 row_mask:0xf bank_mask:0xf
	v_mov_b32_dpp v156, v36 row_ror:8 row_mask:0xf bank_mask:0xf
	v_mov_b32_dpp v157, v37 row_ror:8 row_mask:0xf bank_mask:0xf
	v_mov_b32_dpp v158, v38 row_ror:8 row_mask:0xf bank_mask:0xf
	v_mov_b32_dpp v159, v39 row_ror:8 row_mask:0xf bank_mask:0xf
	v_cndmask_b32_e64 v204, v204, v36, s[40:41]
	v_cndmask_b32_e64 v205, v205, v37, s[40:41]
	v_cndmask_b32_e64 v206, v206, v38, s[40:41]
	v_cndmask_b32_e64 v207, v207, v39, s[40:41]
	v_cndmask_b32_e64 v156, v32, v156, s[40:41]
	v_cndmask_b32_e64 v157, v33, v157, s[40:41]
	v_cndmask_b32_e64 v158, v34, v158, s[40:41]
	v_cndmask_b32_e64 v159, v35, v159, s[40:41]
	global_store_dwordx4 v237, v[204:207], s[30:31] offset:512 nt
	global_store_dwordx4 v149, v[156:159], s[30:31] offset:512 nt
	s_nop 1
	s_waitcnt vmcnt(27)
	v_lshlrev_b32_e32 v156, 16, v208
	v_and_b32_e32 v157, 0xffff0000, v208
	v_lshlrev_b32_e32 v208, 16, v209
	v_and_b32_e32 v209, 0xffff0000, v209
	v_lshlrev_b32_e32 v158, 16, v210
	v_and_b32_e32 v159, 0xffff0000, v210
	v_lshlrev_b32_e32 v210, 16, v211
	v_and_b32_e32 v211, 0xffff0000, v211
	v_pk_add_f32 v[30:31], v[30:31], v[208:209]
	v_pk_add_f32 v[28:29], v[28:29], v[156:157]
	v_pk_add_f32 v[26:27], v[26:27], v[210:211]
	v_pk_add_f32 v[24:25], v[24:25], v[158:159]
	v_add_u32_e32 v149, 0x8000, v238
	s_nop 0
	v_mov_b32_dpp v208, v24 row_ror:8 row_mask:0xf bank_mask:0xf
	v_mov_b32_dpp v209, v25 row_ror:8 row_mask:0xf bank_mask:0xf
	v_mov_b32_dpp v210, v26 row_ror:8 row_mask:0xf bank_mask:0xf
	v_mov_b32_dpp v211, v27 row_ror:8 row_mask:0xf bank_mask:0xf
	v_mov_b32_dpp v156, v28 row_ror:8 row_mask:0xf bank_mask:0xf
	v_mov_b32_dpp v157, v29 row_ror:8 row_mask:0xf bank_mask:0xf
	v_mov_b32_dpp v158, v30 row_ror:8 row_mask:0xf bank_mask:0xf
	v_mov_b32_dpp v159, v31 row_ror:8 row_mask:0xf bank_mask:0xf
	v_cndmask_b32_e64 v208, v208, v28, s[40:41]
	v_cndmask_b32_e64 v209, v209, v29, s[40:41]
	v_cndmask_b32_e64 v210, v210, v30, s[40:41]
	v_cndmask_b32_e64 v211, v211, v31, s[40:41]
	v_cndmask_b32_e64 v156, v24, v156, s[40:41]
	v_cndmask_b32_e64 v157, v25, v157, s[40:41]
	v_cndmask_b32_e64 v158, v26, v158, s[40:41]
	v_cndmask_b32_e64 v159, v27, v159, s[40:41]
	global_store_dwordx4 v238, v[208:211], s[30:31] nt
	global_store_dwordx4 v149, v[156:159], s[30:31] nt
	s_nop 1
	s_waitcnt vmcnt(28)
	v_lshlrev_b32_e32 v156, 16, v212
	v_and_b32_e32 v157, 0xffff0000, v212
	v_lshlrev_b32_e32 v212, 16, v213
	v_and_b32_e32 v213, 0xffff0000, v213
	v_lshlrev_b32_e32 v158, 16, v214
	v_and_b32_e32 v159, 0xffff0000, v214
	v_lshlrev_b32_e32 v214, 16, v215
	v_and_b32_e32 v215, 0xffff0000, v215
	v_pk_add_f32 v[22:23], v[22:23], v[212:213]
	v_pk_add_f32 v[20:21], v[20:21], v[156:157]
	v_pk_add_f32 v[18:19], v[18:19], v[214:215]
	v_pk_add_f32 v[16:17], v[16:17], v[158:159]
	v_add_u32_e32 v149, 0x8000, v238
	s_nop 0
	v_mov_b32_dpp v212, v16 row_ror:8 row_mask:0xf bank_mask:0xf
	v_mov_b32_dpp v213, v17 row_ror:8 row_mask:0xf bank_mask:0xf
	v_mov_b32_dpp v214, v18 row_ror:8 row_mask:0xf bank_mask:0xf
	v_mov_b32_dpp v215, v19 row_ror:8 row_mask:0xf bank_mask:0xf
	v_mov_b32_dpp v156, v20 row_ror:8 row_mask:0xf bank_mask:0xf
	v_mov_b32_dpp v157, v21 row_ror:8 row_mask:0xf bank_mask:0xf
	v_mov_b32_dpp v158, v22 row_ror:8 row_mask:0xf bank_mask:0xf
	v_mov_b32_dpp v159, v23 row_ror:8 row_mask:0xf bank_mask:0xf
	v_cndmask_b32_e64 v212, v212, v20, s[40:41]
	v_cndmask_b32_e64 v213, v213, v21, s[40:41]
	v_cndmask_b32_e64 v214, v214, v22, s[40:41]
	v_cndmask_b32_e64 v215, v215, v23, s[40:41]
	v_cndmask_b32_e64 v156, v16, v156, s[40:41]
	v_cndmask_b32_e64 v157, v17, v157, s[40:41]
	v_cndmask_b32_e64 v158, v18, v158, s[40:41]
	v_cndmask_b32_e64 v159, v19, v159, s[40:41]
	global_store_dwordx4 v238, v[212:215], s[30:31] offset:512 nt
	global_store_dwordx4 v149, v[156:159], s[30:31] offset:512 nt
	s_nop 1
	s_waitcnt vmcnt(29)
	v_lshlrev_b32_e32 v156, 16, v216
	v_and_b32_e32 v157, 0xffff0000, v216
	v_lshlrev_b32_e32 v216, 16, v217
	v_and_b32_e32 v217, 0xffff0000, v217
	v_lshlrev_b32_e32 v158, 16, v218
	v_and_b32_e32 v159, 0xffff0000, v218
	v_lshlrev_b32_e32 v218, 16, v219
	v_and_b32_e32 v219, 0xffff0000, v219
	v_pk_add_f32 v[14:15], v[14:15], v[216:217]
	v_pk_add_f32 v[12:13], v[12:13], v[156:157]
	v_pk_add_f32 v[10:11], v[10:11], v[218:219]
	v_pk_add_f32 v[8:9], v[8:9], v[158:159]
	v_add_u32_e32 v149, 0x8000, v239
	s_nop 0
	v_mov_b32_dpp v216, v8 row_ror:8 row_mask:0xf bank_mask:0xf
	v_mov_b32_dpp v217, v9 row_ror:8 row_mask:0xf bank_mask:0xf
	v_mov_b32_dpp v218, v10 row_ror:8 row_mask:0xf bank_mask:0xf
	v_mov_b32_dpp v219, v11 row_ror:8 row_mask:0xf bank_mask:0xf
	v_mov_b32_dpp v156, v12 row_ror:8 row_mask:0xf bank_mask:0xf
	v_mov_b32_dpp v157, v13 row_ror:8 row_mask:0xf bank_mask:0xf
	v_mov_b32_dpp v158, v14 row_ror:8 row_mask:0xf bank_mask:0xf
	v_mov_b32_dpp v159, v15 row_ror:8 row_mask:0xf bank_mask:0xf
	v_cndmask_b32_e64 v216, v216, v12, s[40:41]
	v_cndmask_b32_e64 v217, v217, v13, s[40:41]
	v_cndmask_b32_e64 v218, v218, v14, s[40:41]
	v_cndmask_b32_e64 v219, v219, v15, s[40:41]
	v_cndmask_b32_e64 v156, v8, v156, s[40:41]
	v_cndmask_b32_e64 v157, v9, v157, s[40:41]
	v_cndmask_b32_e64 v158, v10, v158, s[40:41]
	v_cndmask_b32_e64 v159, v11, v159, s[40:41]
	global_store_dwordx4 v239, v[216:219], s[30:31] nt
	global_store_dwordx4 v149, v[156:159], s[30:31] nt
	s_nop 1
	s_waitcnt vmcnt(30)
	v_lshlrev_b32_e32 v156, 16, v220
	v_and_b32_e32 v157, 0xffff0000, v220
	v_lshlrev_b32_e32 v220, 16, v221
	v_and_b32_e32 v221, 0xffff0000, v221
	v_lshlrev_b32_e32 v158, 16, v222
	v_and_b32_e32 v159, 0xffff0000, v222
	v_lshlrev_b32_e32 v222, 16, v223
	v_and_b32_e32 v223, 0xffff0000, v223
	v_pk_add_f32 v[6:7], v[6:7], v[220:221]
	v_pk_add_f32 v[4:5], v[4:5], v[156:157]
	v_pk_add_f32 v[2:3], v[2:3], v[222:223]
	v_pk_add_f32 v[0:1], v[0:1], v[158:159]
	v_add_u32_e32 v149, 0x8000, v239
	s_nop 0
	v_mov_b32_dpp v220, v0 row_ror:8 row_mask:0xf bank_mask:0xf
	v_mov_b32_dpp v221, v1 row_ror:8 row_mask:0xf bank_mask:0xf
	v_mov_b32_dpp v222, v2 row_ror:8 row_mask:0xf bank_mask:0xf
	v_mov_b32_dpp v223, v3 row_ror:8 row_mask:0xf bank_mask:0xf
	v_mov_b32_dpp v156, v4 row_ror:8 row_mask:0xf bank_mask:0xf
	v_mov_b32_dpp v157, v5 row_ror:8 row_mask:0xf bank_mask:0xf
	v_mov_b32_dpp v158, v6 row_ror:8 row_mask:0xf bank_mask:0xf
	v_mov_b32_dpp v159, v7 row_ror:8 row_mask:0xf bank_mask:0xf
	v_cndmask_b32_e64 v220, v220, v4, s[40:41]
	v_cndmask_b32_e64 v221, v221, v5, s[40:41]
	v_cndmask_b32_e64 v222, v222, v6, s[40:41]
	v_cndmask_b32_e64 v223, v223, v7, s[40:41]
	v_cndmask_b32_e64 v156, v0, v156, s[40:41]
	v_cndmask_b32_e64 v157, v1, v157, s[40:41]
	v_cndmask_b32_e64 v158, v2, v158, s[40:41]
	v_cndmask_b32_e64 v159, v3, v159, s[40:41]
	global_store_dwordx4 v239, v[220:223], s[30:31] offset:512 nt
	global_store_dwordx4 v149, v[156:159], s[30:31] offset:512 nt
	s_nop 1
	s_cbranch_vccnz .LBB0_750
	s_andn2_b64 vcc, exec, s[4:5]
	s_cbranch_vccnz .LBB0_749
	s_barrier
	s_branch .LBB0_749
